# stale-max threshold + exp/PV chunk overlap in masked tiles, padded (unreachable s_nop) so hot loops sit at the same offsets mod 256 as v069
# speedup vs baseline: 1.0051x; 1.0038x over previous
; __device__ __forceinline__ void attn_unit(int uv, const float* sink_l, const bf16_t* P, bf16_t* Y, ATT_LAS unsigned char* lds, const float* rpb_l, const float* qn_l, const float* kn_l) {
;     ...
;     if (a.mode != 0 && nlat > 0) {
.LBB0_644:
	s_xor_b64 s[2:3], s[24:25], -1
	s_cmp_gt_i32 s71, 0
	s_cselect_b64 s[0:1], -1, 0
	s_and_b64 s[0:1], s[4:5], s[0:1]
	s_andn2_b64 vcc, exec, s[0:1]
	s_waitcnt lgkmcnt(0)
	s_cbranch_vccnz .LBB0_536
	s_branch .Lmk_entry
	s_nop 0
	s_nop 0
	s_nop 0
	s_nop 0
	s_nop 0
	s_nop 0
	s_nop 0
	s_nop 0
	s_nop 0
	s_nop 0
	s_nop 0
	s_nop 0
	s_nop 0
	s_nop 0
	s_nop 0
	s_nop 0
	s_nop 0
	s_nop 0
	s_nop 0
	s_nop 0
	s_nop 0
	s_nop 0
	s_nop 0
	s_nop 0
	s_nop 0
	s_nop 0
	s_nop 0
	s_nop 0
	s_nop 0
	s_nop 0
	s_nop 0
	s_nop 0
	s_nop 0

; __device__ __forceinline__ void attn_unit(int uv, const float* sink_l, const bf16_t* P, bf16_t* Y, ATT_LAS unsigned char* lds, const float* rpb_l, const float* qn_l, const float* kn_l) {
;     ...
;         for (int t = 0; t < nlat; ++t) {
;             const int cur = t & 1, tl = a.t_lo + t;
;             if (t + 1 < nlat) { const size_t ro = (size_t)ATT_TROW(t + 5) * PITCH; kreg = *(const u32x4*)(kg + ro); vreg = *(const u32x4*)(vg + ro); }
.LBB0_699:
	s_lshl_b32 s2, s93, 6
	s_add_i32 s2, s2, s27
	s_add_i32 s2, s2, 64
	v_mad_i64_i32 v[32:33], s[2:3], s2, v215, v[198:199]
	global_load_dwordx4 v[120:123], v[32:33], off
	s_andn2_b64 vcc, exec, s[0:1]
	s_cbranch_vccz .LBB0_622
	s_branch .LBB0_623
	s_nop 0
	s_nop 0
	s_nop 0
	s_nop 0
	s_nop 0
	s_nop 0
	s_nop 0
	s_nop 0
	s_nop 0
	s_nop 0
	s_nop 0
	s_nop 0
	s_nop 0
	s_nop 0
	s_nop 0
	s_nop 0
	s_nop 0
	s_nop 0
	s_nop 0
	s_nop 0
	s_nop 0
	s_nop 0
	s_nop 0
	s_nop 0
	s_nop 0
	s_nop 0
	s_nop 0
	s_nop 0
	s_nop 0
	s_nop 0
	s_nop 0
	s_nop 0
	s_nop 0
	s_nop 0
	s_nop 0
	s_nop 0
	s_nop 0
	s_nop 0
	s_nop 0
	s_nop 0
	s_nop 0
	s_nop 0
